# attention loops: row-max tree without the self-max canonicalisation ops and row-sum chain started from the first add (5 VALU fewer per KV tile)
# baseline (speedup 1.0000x reference)
.LBB0_423:
	s_lshl_b32 s16, s19, 14
	s_add_i32 s4, s16, 16
	v_add_u32_e32 v96, s4, v185
	ds_read_b128 v[198:201], v96 offset:49152
	ds_read_b128 v[202:205], v96 offset:57344
	v_xor_b32_e32 v80, 0x80000000, v195
	v_mov_b32_e32 v81, v80
	v_mov_b64_e32 v[82:83], v[80:81]
	v_mov_b64_e32 v[84:85], v[80:81]
	v_mov_b64_e32 v[86:87], v[80:81]
	v_mov_b64_e32 v[88:89], v[80:81]
	v_mov_b64_e32 v[90:91], v[80:81]
	v_mov_b64_e32 v[92:93], v[80:81]
	v_mov_b64_e32 v[94:95], v[80:81]
	v_exp_f32_e32 v221, v64
	s_waitcnt lgkmcnt(1)
	v_mfma_f32_32x32x16_bf16 v[96:111], v[198:201], v[124:127], v[80:95]
	v_add_f32_e32 v64, v153, v152
	v_add_f32_e32 v64, v154, v64
	v_add_u32_e32 v197, s4, v189
	v_add_f32_e32 v64, v155, v64
	v_add_f32_e32 v64, v156, v64
	v_add_f32_e32 v64, v157, v64
	v_add_f32_e32 v64, v158, v64
	s_waitcnt lgkmcnt(0)
	v_mfma_f32_32x32x16_bf16 v[80:95], v[202:205], v[124:127], v[80:95]
	ds_read_b128 v[198:201], v197 offset:49152
	ds_read_b128 v[202:205], v197 offset:57344
	v_add_f32_e32 v64, v159, v64
	v_add_f32_e32 v64, v144, v64
	v_add_f32_e32 v64, v145, v64
	v_add_f32_e32 v64, v146, v64
	v_add_u32_e32 v197, s4, v192
	v_add_f32_e32 v64, v147, v64
	s_waitcnt lgkmcnt(1)
	v_mfma_f32_32x32x16_bf16 v[96:111], v[198:201], v[120:123], v[96:111]
	ds_read_b128 v[198:201], v197 offset:49152
	ds_read_b128 v[206:209], v197 offset:57344
	v_add_f32_e32 v64, v148, v64
	v_exp_f32_e32 v222, v65
	v_add_f32_e32 v64, v149, v64
	v_exp_f32_e32 v223, v66
	v_add_f32_e32 v64, v150, v64
	v_exp_f32_e32 v224, v67
	s_waitcnt lgkmcnt(2)
	v_mfma_f32_32x32x16_bf16 v[80:95], v[202:205], v[120:123], v[80:95]
	v_add_f32_e32 v64, v151, v64
	v_add_f32_e32 v64, v221, v64
	v_add_f32_e32 v64, v222, v64
	v_add_f32_e32 v64, v223, v64
	v_exp_f32_e32 v71, v71
	v_add_f32_e32 v64, v224, v64
	v_add_u32_e32 v197, s4, v194
	s_waitcnt lgkmcnt(1)
	v_mfma_f32_32x32x16_bf16 v[96:111], v[198:201], v[116:119], v[96:111]
	v_exp_f32_e32 v199, v68
	v_exp_f32_e32 v200, v69
	v_exp_f32_e32 v201, v70
	v_exp_f32_e32 v225, v72
	v_add_f32_e32 v64, v199, v64
	ds_read_b128 v[202:205], v197 offset:49152
	ds_read_b128 v[210:213], v197 offset:57344
	v_exp_f32_e32 v226, v73
	s_waitcnt lgkmcnt(2)
	v_mfma_f32_32x32x16_bf16 v[80:95], v[206:209], v[116:119], v[80:95]
	v_add_f32_e32 v64, v200, v64
	v_exp_f32_e32 v227, v74
	v_add_f32_e32 v64, v201, v64
	v_exp_f32_e32 v206, v75
	v_add_f32_e32 v64, v71, v64
	v_exp_f32_e32 v207, v76
	v_add_f32_e32 v64, v225, v64
	v_exp_f32_e32 v208, v77
	v_add_f32_e32 v64, v226, v64
	v_exp_f32_e32 v209, v78
	s_waitcnt lgkmcnt(1)
	v_mfma_f32_32x32x16_bf16 v[96:111], v[202:205], v[112:115], v[96:111]
	v_add_f32_e32 v64, v227, v64
	v_exp_f32_e32 v79, v79
	v_add_f32_e32 v64, v206, v64
	v_add_f32_e32 v64, v207, v64
	v_add_f32_e32 v64, v208, v64
	v_add_f32_e32 v64, v209, v64
	v_add_f32_e32 v197, v79, v64
	s_waitcnt lgkmcnt(0)
	v_mfma_f32_32x32x16_bf16 v[80:95], v[210:213], v[112:115], v[80:95]
	v_mov_b32_e32 v198, v197
	v_cvt_pk_bf16_f32 v64, v152, v153
	v_cvt_pk_bf16_f32 v65, v154, v155
	v_cvt_pk_bf16_f32 v66, v156, v157
	v_cvt_pk_bf16_f32 v67, v158, v159
	v_cvt_pk_bf16_f32 v72, v144, v145
	v_cvt_pk_bf16_f32 v73, v146, v147
	v_cvt_pk_bf16_f32 v74, v148, v149
	v_cvt_pk_bf16_f32 v75, v150, v151
	v_cvt_pk_bf16_f32 v68, v221, v222
	v_cvt_pk_bf16_f32 v69, v223, v224
	v_cvt_pk_bf16_f32 v70, v199, v200
	v_cvt_pk_bf16_f32 v71, v201, v71
	v_cvt_pk_bf16_f32 v76, v225, v226
	v_cvt_pk_bf16_f32 v77, v227, v206
	v_cvt_pk_bf16_f32 v78, v207, v208
	v_cvt_pk_bf16_f32 v79, v209, v79
	v_permlane32_swap_b32_e32 v197, v198
	v_permlane32_swap_b32_e32 v64, v66
	v_permlane32_swap_b32_e32 v65, v67
	v_permlane32_swap_b32_e32 v72, v74
	v_permlane32_swap_b32_e32 v73, v75
	v_permlane32_swap_b32_e32 v68, v70
	v_permlane32_swap_b32_e32 v69, v71
	v_permlane32_swap_b32_e32 v76, v78
	v_permlane32_swap_b32_e32 v77, v79
	global_load_dwordx4 v[144:147], v244, s[98:99]
	global_load_dwordx4 v[148:151], v245, s[98:99]
	global_load_dwordx4 v[152:155], v242, s[98:99]
	global_load_dwordx4 v[156:159], v243, s[98:99]
	s_add_u32 s98, s98, 0x10000
	s_addc_u32 s99, s99, 0
	v_lshl_add_u32 v199, s18, 14, v181
	ds_read_b64_tr_b16 v[200:201], v199 offset:0
	ds_read_b64_tr_b16 v[202:203], v199 offset:0x800
	ds_read_b64_tr_b16 v[204:205], v199 offset:0x1000
	ds_read_b64_tr_b16 v[206:207], v199 offset:0x1800
	ds_read_b64_tr_b16 v[208:209], v199 offset:0x2000
	ds_read_b64_tr_b16 v[210:211], v199 offset:0x2800
	ds_read_b64_tr_b16 v[222:223], v199 offset:0x3000
	ds_read_b64_tr_b16 v[224:225], v199 offset:0x3800
	s_waitcnt lgkmcnt(0)
	s_nop 0
	v_mfma_f32_32x32x16_bf16 v[0:15], v[64:67], v[200:203], v[0:15]
	v_max_f32_e32 v200, v96, v97
	v_max3_f32 v200, v200, v98, v99
	v_max3_f32 v200, v200, v100, v101
	v_max3_f32 v200, v200, v102, v103
	v_max3_f32 v200, v200, v104, v105
	v_mfma_f32_32x32x16_bf16 v[0:15], v[72:75], v[204:207], v[0:15]
	v_max3_f32 v200, v200, v106, v107
	v_max3_f32 v202, v200, v108, v109
	ds_read_b64_tr_b16 v[200:201], v199 offset:0x200
	v_max3_f32 v212, v202, v110, v111
	ds_read_b64_tr_b16 v[202:203], v199 offset:0xa00
	ds_read_b64_tr_b16 v[204:205], v199 offset:0x1200
	ds_read_b64_tr_b16 v[206:207], v199 offset:0x1a00
	v_mfma_f32_32x32x16_bf16 v[0:15], v[68:71], v[208:211], v[0:15]
	ds_read_b64_tr_b16 v[208:209], v199 offset:0x2200
	ds_read_b64_tr_b16 v[210:211], v199 offset:0x2a00
	ds_read_b64_tr_b16 v[226:227], v199 offset:0x3200
	ds_read_b64_tr_b16 v[228:229], v199 offset:0x3a00
	s_waitcnt lgkmcnt(0)
	v_mfma_f32_32x32x16_bf16 v[0:15], v[76:79], v[222:225], v[0:15]
	v_mfma_f32_32x32x16_bf16 v[48:63], v[64:67], v[200:203], v[48:63]
	v_max3_f32 v212, v212, v80, v81
	v_max3_f32 v200, v212, v82, v83
	ds_read_b64_tr_b16 v[202:203], v199 offset:0x400
	v_max3_f32 v200, v200, v84, v85
	v_max3_f32 v200, v200, v86, v87
	v_max3_f32 v200, v200, v88, v89
	v_max3_f32 v200, v200, v90, v91
	v_mfma_f32_32x32x16_bf16 v[48:63], v[72:75], v[204:207], v[48:63]
	ds_read_b64_tr_b16 v[204:205], v199 offset:0xc00
	ds_read_b64_tr_b16 v[206:207], v199 offset:0x1400
	v_max3_f32 v200, v200, v92, v93
	v_max3_f32 v200, v200, v94, v95
	v_mov_b32_e32 v201, v200
	s_nop 1
	v_permlane32_swap_b32_e32 v200, v201
	v_mfma_f32_32x32x16_bf16 v[48:63], v[68:71], v[208:211], v[48:63]
	ds_read_b64_tr_b16 v[208:209], v199 offset:0x1c00
	ds_read_b64_tr_b16 v[210:211], v199 offset:0x2400
	ds_read_b64_tr_b16 v[212:213], v199 offset:0x2c00
	ds_read_b64_tr_b16 v[222:223], v199 offset:0x3400
	ds_read_b64_tr_b16 v[224:225], v199 offset:0x3c00
	s_waitcnt lgkmcnt(0)
	v_mfma_f32_32x32x16_bf16 v[48:63], v[76:79], v[226:229], v[48:63]
	v_max_f32_e32 v200, v200, v201
	v_mfma_f32_32x32x16_bf16 v[32:47], v[64:67], v[202:205], v[32:47]
	v_cmp_ge_f32_e32 vcc, s63, v200
	s_cmp_eq_u64 vcc, exec
	v_mfma_f32_32x32x16_bf16 v[32:47], v[72:75], v[206:209], v[32:47]
	v_mfma_f32_32x32x16_bf16 v[32:47], v[68:71], v[210:213], v[32:47]
	v_mfma_f32_32x32x16_bf16 v[32:47], v[76:79], v[222:225], v[32:47]
	s_cbranch_scc0 .LBB0_438
	v_mov_b32_e32 v200, 1.0

.LBB0_429:
	v_exp_f32_e32 v199, v96
	v_exp_f32_e32 v221, v97
	v_exp_f32_e32 v226, v98
	v_exp_f32_e32 v227, v99
	v_exp_f32_e32 v228, v100
	v_exp_f32_e32 v229, v101
	v_exp_f32_e32 v230, v102
	v_exp_f32_e32 v231, v103
	v_exp_f32_e32 v232, v104
	v_exp_f32_e32 v233, v105
	v_exp_f32_e32 v234, v106
	v_exp_f32_e32 v235, v107
	v_exp_f32_e32 v236, v108
	v_exp_f32_e32 v237, v109
	v_exp_f32_e32 v238, v110
	v_exp_f32_e32 v239, v111
	s_waitcnt lgkmcnt(0)
	s_barrier
	v_add_u32_e32 v96, s17, v185
	ds_read_b128 v[202:205], v96 offset:49152
	ds_read_b128 v[206:209], v96 offset:57344
	v_xor_b32_e32 v64, 0x80000000, v195
	v_mov_b32_e32 v65, v64
	v_mov_b64_e32 v[66:67], v[64:65]
	v_mov_b64_e32 v[68:69], v[64:65]
	v_mov_b64_e32 v[70:71], v[64:65]
	v_mov_b64_e32 v[72:73], v[64:65]
	v_mov_b64_e32 v[74:75], v[64:65]
	v_mov_b64_e32 v[76:77], v[64:65]
	v_mov_b64_e32 v[78:79], v[64:65]
	v_add_u32_e32 v201, s17, v189
	v_exp_f32_e32 v80, v80
	s_waitcnt lgkmcnt(1)
	v_mfma_f32_32x32x16_bf16 v[96:111], v[202:205], v[124:127], v[64:79]
	v_exp_f32_e32 v81, v81
	v_exp_f32_e32 v82, v82
	v_exp_f32_e32 v83, v83
	v_exp_f32_e32 v84, v84
	v_exp_f32_e32 v85, v85
	v_exp_f32_e32 v86, v86
	v_exp_f32_e32 v87, v87
	s_waitcnt lgkmcnt(0)
	v_mfma_f32_32x32x16_bf16 v[64:79], v[206:209], v[124:127], v[64:79]
	ds_read_b128 v[202:205], v201 offset:49152
	ds_read_b128 v[206:209], v201 offset:57344
	v_add_u32_e32 v201, s17, v192
	v_exp_f32_e32 v240, v91
	v_exp_f32_e32 v241, v92
	v_cvt_pk_bf16_f32 v91, v230, v231
	v_cvt_pk_bf16_f32 v92, v232, v233
	s_waitcnt lgkmcnt(1)
	v_mfma_f32_32x32x16_bf16 v[96:111], v[202:205], v[120:123], v[96:111]
	ds_read_b128 v[202:205], v201 offset:49152
	ds_read_b128 v[210:213], v201 offset:57344
	v_add_u32_e32 v201, s17, v194
	s_waitcnt lgkmcnt(1)
	v_mfma_f32_32x32x16_bf16 v[96:111], v[202:205], v[116:119], v[96:111]
	v_exp_f32_e32 v203, v88
	v_add_f32_e32 v88, v221, v199
	v_add_f32_e32 v88, v226, v88
	v_add_f32_e32 v88, v227, v88
	v_add_f32_e32 v88, v228, v88
	v_add_f32_e32 v88, v229, v88
	v_add_f32_e32 v88, v230, v88
	v_add_f32_e32 v88, v231, v88
	v_add_f32_e32 v88, v232, v88
	v_add_f32_e32 v88, v233, v88
	v_mfma_f32_32x32x16_bf16 v[64:79], v[206:209], v[120:123], v[64:79]
	v_add_f32_e32 v88, v234, v88
	v_add_f32_e32 v88, v235, v88
	v_add_f32_e32 v88, v236, v88
	v_add_f32_e32 v88, v237, v88
	v_add_f32_e32 v88, v238, v88
	v_add_f32_e32 v88, v239, v88
	v_add_f32_e32 v88, v80, v88
	v_add_f32_e32 v88, v81, v88
	s_waitcnt lgkmcnt(0)
	v_mfma_f32_32x32x16_bf16 v[64:79], v[210:213], v[116:119], v[64:79]
	v_add_f32_e32 v88, v82, v88
	v_add_f32_e32 v88, v83, v88
	v_add_f32_e32 v88, v84, v88
	ds_read_b128 v[206:209], v201 offset:49152
	ds_read_b128 v[222:225], v201 offset:57344
	v_exp_f32_e32 v204, v89
	v_add_f32_e32 v88, v85, v88
	v_exp_f32_e32 v205, v90
	v_add_f32_e32 v88, v86, v88
	v_add_f32_e32 v88, v87, v88
	v_add_f32_e32 v88, v203, v88
	v_exp_f32_e32 v210, v93
	v_add_f32_e32 v88, v204, v88
	v_exp_f32_e32 v211, v94
	s_waitcnt lgkmcnt(1)
	v_mfma_f32_32x32x16_bf16 v[96:111], v[206:209], v[112:115], v[96:111]
	v_add_f32_e32 v88, v205, v88
	v_exp_f32_e32 v212, v95
	v_add_f32_e32 v88, v240, v88
	v_add_f32_e32 v88, v241, v88
	v_add_f32_e32 v88, v210, v88
	v_add_f32_e32 v88, v211, v88
	v_add_f32_e32 v201, v212, v88
	s_waitcnt lgkmcnt(0)
	v_mfma_f32_32x32x16_bf16 v[64:79], v[222:225], v[112:115], v[64:79]
	v_mov_b32_e32 v202, v201
	v_cvt_pk_bf16_f32 v88, v199, v221
	v_cvt_pk_bf16_f32 v89, v226, v227
	v_cvt_pk_bf16_f32 v90, v228, v229
	v_cvt_pk_bf16_f32 v93, v234, v235
	v_cvt_pk_bf16_f32 v94, v236, v237
	v_cvt_pk_bf16_f32 v95, v238, v239
	v_cvt_pk_bf16_f32 v80, v80, v81
	v_cvt_pk_bf16_f32 v81, v82, v83
	v_cvt_pk_bf16_f32 v82, v84, v85
	v_cvt_pk_bf16_f32 v83, v86, v87
	v_cvt_pk_bf16_f32 v84, v203, v204
	v_cvt_pk_bf16_f32 v85, v205, v240
	v_cvt_pk_bf16_f32 v86, v241, v210
	v_cvt_pk_bf16_f32 v87, v211, v212
	v_permlane32_swap_b32_e32 v201, v202
	v_permlane32_swap_b32_e32 v88, v90
	v_permlane32_swap_b32_e32 v89, v91
	v_permlane32_swap_b32_e32 v92, v94
	v_permlane32_swap_b32_e32 v93, v95
	v_permlane32_swap_b32_e32 v80, v82
	v_permlane32_swap_b32_e32 v81, v83
	v_permlane32_swap_b32_e32 v84, v86
	v_permlane32_swap_b32_e32 v85, v87
	s_cmpk_gt_u32 s6, 0x7c
	s_cselect_b64 s[4:5], -1, 0
	s_and_b64 vcc, exec, s[4:5]
	s_cbranch_vccnz .Lattn_a0_lastw
	global_load_dwordx4 v[132:135], v244, s[98:99]
	global_load_dwordx4 v[128:131], v242, s[98:99]
	global_load_dwordx4 v[140:143], v245, s[98:99]
	global_load_dwordx4 v[136:139], v243, s[98:99]
	s_add_u32 s98, s98, 0x10000
	s_addc_u32 s99, s99, 0
.LBB0_431:
	v_add_u32_e32 v203, s16, v181
	ds_read_b64_tr_b16 v[204:205], v203 offset:0
	ds_read_b64_tr_b16 v[206:207], v203 offset:0x800
	ds_read_b64_tr_b16 v[208:209], v203 offset:0x1000
	ds_read_b64_tr_b16 v[210:211], v203 offset:0x1800
	ds_read_b64_tr_b16 v[222:223], v203 offset:0x2000
	ds_read_b64_tr_b16 v[224:225], v203 offset:0x2800
	ds_read_b64_tr_b16 v[226:227], v203 offset:0x3000
	ds_read_b64_tr_b16 v[228:229], v203 offset:0x3800
	s_waitcnt lgkmcnt(0)
	s_nop 0
	v_mfma_f32_32x32x16_bf16 v[0:15], v[88:91], v[204:207], v[0:15]
	v_max_f32_e32 v199, v96, v97
	ds_read_b64_tr_b16 v[204:205], v203 offset:0x200
	ds_read_b64_tr_b16 v[206:207], v203 offset:0xa00
	v_max3_f32 v199, v199, v98, v99
	v_max3_f32 v199, v199, v100, v101
	v_mfma_f32_32x32x16_bf16 v[0:15], v[92:95], v[208:211], v[0:15]
	ds_read_b64_tr_b16 v[208:209], v203 offset:0x1200
	ds_read_b64_tr_b16 v[210:211], v203 offset:0x1a00
	v_max3_f32 v199, v199, v102, v103
	v_max3_f32 v199, v199, v104, v105
	v_max3_f32 v199, v199, v106, v107
	v_max3_f32 v199, v199, v108, v109
	v_max3_f32 v199, v199, v110, v111
	v_mfma_f32_32x32x16_bf16 v[0:15], v[80:83], v[222:225], v[0:15]
	ds_read_b64_tr_b16 v[222:223], v203 offset:0x2200
	ds_read_b64_tr_b16 v[224:225], v203 offset:0x2a00
	ds_read_b64_tr_b16 v[230:231], v203 offset:0x3200
	ds_read_b64_tr_b16 v[232:233], v203 offset:0x3a00
	s_waitcnt lgkmcnt(0)
	v_mfma_f32_32x32x16_bf16 v[0:15], v[84:87], v[226:229], v[0:15]
	v_mfma_f32_32x32x16_bf16 v[48:63], v[88:91], v[204:207], v[48:63]
	v_max3_f32 v199, v199, v64, v65
	v_max3_f32 v199, v199, v66, v67
	ds_read_b64_tr_b16 v[206:207], v203 offset:0x400
	v_max3_f32 v199, v199, v68, v69
	v_max3_f32 v199, v199, v70, v71
	v_max3_f32 v199, v199, v72, v73
	v_max3_f32 v199, v199, v74, v75
	v_mfma_f32_32x32x16_bf16 v[48:63], v[92:95], v[208:211], v[48:63]
	ds_read_b64_tr_b16 v[208:209], v203 offset:0xc00
	ds_read_b64_tr_b16 v[210:211], v203 offset:0x1400
	ds_read_b64_tr_b16 v[212:213], v203 offset:0x1c00
	v_max3_f32 v199, v199, v76, v77
	v_max3_f32 v199, v199, v78, v79
	v_mov_b32_e32 v204, v199
	s_nop 1
	v_permlane32_swap_b32_e32 v199, v204
	v_mfma_f32_32x32x16_bf16 v[48:63], v[80:83], v[222:225], v[48:63]
	ds_read_b64_tr_b16 v[222:223], v203 offset:0x2400
	ds_read_b64_tr_b16 v[224:225], v203 offset:0x2c00
	ds_read_b64_tr_b16 v[226:227], v203 offset:0x3400
	ds_read_b64_tr_b16 v[228:229], v203 offset:0x3c00
	s_waitcnt lgkmcnt(0)
	v_mfma_f32_32x32x16_bf16 v[48:63], v[84:87], v[230:233], v[48:63]
	v_max_f32_e32 v204, v199, v204
	v_mfma_f32_32x32x16_bf16 v[32:47], v[88:91], v[206:209], v[32:47]
	v_cmp_ge_f32_e32 vcc, s63, v204
	s_cmp_eq_u64 vcc, exec
	v_mov_b32_e32 v199, 1.0
	v_mfma_f32_32x32x16_bf16 v[32:47], v[92:95], v[210:213], v[32:47]
	v_mfma_f32_32x32x16_bf16 v[32:47], v[80:83], v[222:225], v[32:47]
	v_mfma_f32_32x32x16_bf16 v[32:47], v[84:87], v[226:229], v[32:47]
	s_cbranch_scc0 .LBB0_439
